# P1 K loop body: yield point after every 8 MFMAs as well (P1, P4, P5 loops now), on top of v110
# baseline (speedup 1.0000x reference)
; #define PG8_STAGE(bufoff, gbase, voff) do { _Pragma("unroll") for (int _i = 0; _i < 2; ++_i) \
;         __builtin_amdgcn_global_load_lds((const unsigned*)((const char*)(gbase) + (voff)[_i]), (PG8_LAS unsigned*)(lds + (bufoff) + ldsw + _i * 8192), 16, 0, 0); } while (0)
; #define PG8_LDA(dst, b, h) do { _Pragma("unroll") for (int m = 0; m < 4; ++m) _Pragma("unroll") for (int k = 0; k < 2; ++k) dst[m][k] = *(const PG8_LAS bf16x8*)(lds + PG8_SA(b, h) + aoff + m * 2048 + k * 1024); } while (0)
; #define PG8_LDB(dst, b, h) do { _Pragma("unroll") for (int n = 0; n < 2; ++n) _Pragma("unroll") for (int k = 0; k < 2; ++k) dst[n][k] = *(const PG8_LAS bf16x8*)(lds + PG8_SB(b, h) + boff + n * 2048 + k * 1024); } while (0)
; #define PG8_MMA(ai, bj, At, Bt) do { __builtin_amdgcn_s_setprio(1); _Pragma("unroll") for (int m = 0; m < 4; ++m) _Pragma("unroll") for (int n = 0; n < 2; ++n) _Pragma("unroll") for (int k = 0; k < 2; ++k) \
;         acc[ai][bj][m][n] = __builtin_amdgcn_mfma_f32_16x16x32_bf16(Bt[n][k], At[m][k], acc[ai][bj][m][n], 0, 0, 0); __builtin_amdgcn_s_setprio(0); } while (0)
; #define PG8_WAIT_V(n) asm volatile("s_waitcnt vmcnt(" #n ")" ::: "memory")
; #define PG8_WAIT_L(n) asm volatile("s_waitcnt lgkmcnt(" #n ")" ::: "memory")
; template <class Epi, class Sched, bool ALIGN_EPI = false, bool SP2 = false, bool ABLK = false>
; __device__ __forceinline__ void gemm_phase(PG8_LAS unsigned char* lds, const Gemm g, const Sched& S, const Epi& E) {
;     ...
;             const bool last = (t == nt - 2);
;             const char* a1 = cA + (size_t)(t + 1) * kstepA;
;             const char* a2 = last ? nA : cA + (size_t)(t + 2) * kstepA; const char* b2 = last ? nB : cB + (size_t)(t + 2) * kstep;
;             const char* a3 = a2 + kstepA; const char* b3 = b2 + kstep;
;             if (last && has_next) S.a_ready(nxt);
;             if constexpr (SP2) {
;             PG8_LDB(B0, 0, 0); PG8_LDB(B1, 0, 1); PG8_SCHED; PG8_LDA(At, 0, 0); PG8_STAGE(PG8_SA(1, 1), a1 + hstepA, voffA);
;             PG8_WAIT_V(8); PG8_WAIT_L(0); PG8_BAR; PG8_MMA(0, 0, At, B0); PG8_MMA(0, 1, At, B1); PG8_BAR; PG8_SCHED;
;             PG8_LDA(At, 0, 1); PG8_STAGE(PG8_SB(0, 0), b2, voffB); PG8_STAGE(PG8_SB(0, 1), b2 + hstep, voffB); PG8_STAGE(PG8_SA(0, 0), a2, voffA);
;             PG8_WAIT_V(8); PG8_WAIT_L(0); PG8_BAR; PG8_MMA(1, 0, At, B0); PG8_MMA(1, 1, At, B1); PG8_BAR; PG8_SCHED;
.LBB0_215:
	ds_read_b128 v[166:169], v163
	ds_read_b128 v[170:173], v163 offset:1024
	ds_read_b128 v[180:183], v163 offset:2048
	ds_read_b128 v[184:187], v163 offset:3072
	ds_read_b128 v[188:191], v164
	ds_read_b128 v[192:195], v164 offset:1024
	ds_read_b128 v[196:199], v164 offset:2048
	ds_read_b128 v[200:203], v164 offset:3072
	s_add_u32 s0, vcc_lo, 0xfffc0080
	s_addc_u32 s1, vcc_hi, -1
	s_cmp_eq_u32 s25, 12
	s_cselect_b32 s99, s5, s1
	s_cselect_b32 s98, s21, s0
	s_cselect_b32 s1, s95, s24
	s_cselect_b32 s0, s22, s23
	v_lshl_add_u64 v[176:177], vcc, 0, v[142:143]
	s_add_i32 m0, s97, 0xc000
	ds_read_b128 v[204:207], v165
	ds_read_b128 v[208:211], v165 offset:1024
	ds_read_b128 v[212:215], v165 offset:2048
	ds_read_b128 v[216:219], v165 offset:3072
	ds_read_b128 v[220:223], v165 offset:4096
	ds_read_b128 v[224:227], v165 offset:5120
	ds_read_b128 v[228:231], v165 offset:6144
	ds_read_b128 v[232:235], v165 offset:7168
	global_load_lds_dwordx4 v[176:177], off
	v_lshl_add_u64 v[176:177], vcc, 0, v[144:145]
	s_add_i32 m0, s97, 0xe000
	s_nop 0
	global_load_lds_dwordx4 v[176:177], off
	s_waitcnt vmcnt(8)
	s_waitcnt lgkmcnt(0)
	s_barrier
	s_setprio 1
	s_waitcnt lgkmcnt(0)
	v_mfma_f32_16x16x32_bf16 v[124:127], v[166:169], v[204:207], v[124:127]
	v_mfma_f32_16x16x32_bf16 v[120:123], v[180:183], v[204:207], v[120:123]
	v_mfma_f32_16x16x32_bf16 v[116:119], v[166:169], v[212:215], v[116:119]
	v_mfma_f32_16x16x32_bf16 v[108:111], v[180:183], v[212:215], v[108:111]
	v_mfma_f32_16x16x32_bf16 v[100:103], v[166:169], v[220:223], v[100:103]
	v_mfma_f32_16x16x32_bf16 v[92:95], v[180:183], v[220:223], v[92:95]
	v_mfma_f32_16x16x32_bf16 v[84:87], v[166:169], v[228:231], v[84:87]
	v_mfma_f32_16x16x32_bf16 v[76:79], v[180:183], v[228:231], v[76:79]
	s_setprio 0
	s_setprio 1
	v_mfma_f32_16x16x32_bf16 v[124:127], v[170:173], v[208:211], v[124:127]
	v_mfma_f32_16x16x32_bf16 v[120:123], v[184:187], v[208:211], v[120:123]
	v_mfma_f32_16x16x32_bf16 v[116:119], v[170:173], v[216:219], v[116:119]
	v_mfma_f32_16x16x32_bf16 v[108:111], v[184:187], v[216:219], v[108:111]
	v_mfma_f32_16x16x32_bf16 v[100:103], v[170:173], v[224:227], v[100:103]
	v_mfma_f32_16x16x32_bf16 v[92:95], v[184:187], v[224:227], v[92:95]
	v_mfma_f32_16x16x32_bf16 v[84:87], v[170:173], v[232:235], v[84:87]
	v_mfma_f32_16x16x32_bf16 v[76:79], v[184:187], v[232:235], v[76:79]
	s_setprio 0
	s_setprio 1
	v_mfma_f32_16x16x32_bf16 v[112:115], v[188:191], v[204:207], v[112:115]
	v_mfma_f32_16x16x32_bf16 v[104:107], v[196:199], v[204:207], v[104:107]
	v_mfma_f32_16x16x32_bf16 v[96:99], v[188:191], v[212:215], v[96:99]
	v_mfma_f32_16x16x32_bf16 v[88:91], v[196:199], v[212:215], v[88:91]
	v_mfma_f32_16x16x32_bf16 v[80:83], v[188:191], v[220:223], v[80:83]
	v_mfma_f32_16x16x32_bf16 v[72:75], v[196:199], v[220:223], v[72:75]
	v_mfma_f32_16x16x32_bf16 v[68:71], v[188:191], v[228:231], v[68:71]
	v_mfma_f32_16x16x32_bf16 v[64:67], v[196:199], v[228:231], v[64:67]
	s_setprio 0
	s_setprio 1
	v_mfma_f32_16x16x32_bf16 v[112:115], v[192:195], v[208:211], v[112:115]
	v_mfma_f32_16x16x32_bf16 v[104:107], v[200:203], v[208:211], v[104:107]
	v_mfma_f32_16x16x32_bf16 v[96:99], v[192:195], v[216:219], v[96:99]
	v_mfma_f32_16x16x32_bf16 v[88:91], v[200:203], v[216:219], v[88:91]
	v_mfma_f32_16x16x32_bf16 v[80:83], v[192:195], v[224:227], v[80:83]
	v_mfma_f32_16x16x32_bf16 v[72:75], v[200:203], v[224:227], v[72:75]
	v_mfma_f32_16x16x32_bf16 v[68:71], v[192:195], v[232:235], v[68:71]
	v_mfma_f32_16x16x32_bf16 v[64:67], v[200:203], v[232:235], v[64:67]
	s_setprio 0
	s_barrier
	s_add_i32 s26, s17, s46
	v_lshl_add_u64 v[176:177], s[0:1], 0, v[136:137]
	s_mov_b32 m0, s26
	ds_read_b128 v[204:207], v165 offset:16384
	ds_read_b128 v[208:211], v165 offset:17408
	ds_read_b128 v[212:215], v165 offset:18432
	ds_read_b128 v[216:219], v165 offset:19456
	ds_read_b128 v[220:223], v165 offset:20480
	ds_read_b128 v[224:227], v165 offset:21504
	ds_read_b128 v[228:231], v165 offset:22528
	ds_read_b128 v[232:235], v165 offset:23552
	global_load_lds_dwordx4 v[176:177], off
	s_add_i32 m0, s26, 0x2000
	s_add_u32 s26, s0, 0x40000
	v_lshl_add_u64 v[236:237], s[0:1], 0, v[132:133]
	s_addc_u32 s27, s1, 0
	s_add_i32 s28, s18, s46
	global_load_lds_dwordx4 v[236:237], off
	v_lshl_add_u64 v[238:239], s[26:27], 0, v[136:137]
	s_mov_b32 m0, s28
	v_lshl_add_u64 v[240:241], s[98:99], 0, v[134:135]
	global_load_lds_dwordx4 v[238:239], off
	v_lshl_add_u64 v[238:239], s[26:27], 0, v[132:133]
	s_add_i32 m0, s28, 0x2000
	s_nop 0
	global_load_lds_dwordx4 v[238:239], off
	v_lshl_add_u64 v[238:239], s[98:99], 0, v[138:139]
	s_mov_b32 m0, s97
	s_nop 0
	global_load_lds_dwordx4 v[238:239], off
	s_mov_b32 m0, s10
	s_nop 0
	global_load_lds_dwordx4 v[240:241], off
	s_waitcnt vmcnt(8)
	s_waitcnt lgkmcnt(0)
	s_barrier
; #define PG8_STAGE(bufoff, gbase, voff) do { _Pragma("unroll") for (int _i = 0; _i < 2; ++_i) \
;         __builtin_amdgcn_global_load_lds((const unsigned*)((const char*)(gbase) + (voff)[_i]), (PG8_LAS unsigned*)(lds + (bufoff) + ldsw + _i * 8192), 16, 0, 0); } while (0)
; #define PG8_LDA(dst, b, h) do { _Pragma("unroll") for (int m = 0; m < 4; ++m) _Pragma("unroll") for (int k = 0; k < 2; ++k) dst[m][k] = *(const PG8_LAS bf16x8*)(lds + PG8_SA(b, h) + aoff + m * 2048 + k * 1024); } while (0)
; #define PG8_LDB(dst, b, h) do { _Pragma("unroll") for (int n = 0; n < 2; ++n) _Pragma("unroll") for (int k = 0; k < 2; ++k) dst[n][k] = *(const PG8_LAS bf16x8*)(lds + PG8_SB(b, h) + boff + n * 2048 + k * 1024); } while (0)
; #define PG8_MMA(ai, bj, At, Bt) do { __builtin_amdgcn_s_setprio(1); _Pragma("unroll") for (int m = 0; m < 4; ++m) _Pragma("unroll") for (int n = 0; n < 2; ++n) _Pragma("unroll") for (int k = 0; k < 2; ++k) \
;         acc[ai][bj][m][n] = __builtin_amdgcn_mfma_f32_16x16x32_bf16(Bt[n][k], At[m][k], acc[ai][bj][m][n], 0, 0, 0); __builtin_amdgcn_s_setprio(0); } while (0)
; #define PG8_WAIT_V(n) asm volatile("s_waitcnt vmcnt(" #n ")" ::: "memory")
; #define PG8_WAIT_L(n) asm volatile("s_waitcnt lgkmcnt(" #n ")" ::: "memory")
; #define PG8_BAR __builtin_amdgcn_s_barrier()
; #define PG8_SCHED __builtin_amdgcn_sched_barrier(0)
; template <class Epi, class Sched, bool ALIGN_EPI = false, bool SP2 = false, bool ABLK = false>
; __device__ __forceinline__ void gemm_phase(PG8_LAS unsigned char* lds, const Gemm g, const Sched& S, const Epi& E) {
;     ...
;             PG8_WAIT_V(8); PG8_WAIT_L(0); PG8_BAR; PG8_MMA(1, 0, At, B0); PG8_MMA(1, 1, At, B1); PG8_BAR; PG8_SCHED;
;             PG8_LDB(B0, 1, 0); PG8_LDB(B1, 1, 1); PG8_SCHED; PG8_LDA(At, 1, 0); PG8_STAGE(PG8_SA(0, 1), a2 + hstepA, voffA);
;             PG8_WAIT_V(8); PG8_WAIT_L(0); PG8_BAR; PG8_MMA(0, 0, At, B0); PG8_MMA(0, 1, At, B1); PG8_BAR; PG8_SCHED;
	s_setprio 1
	s_waitcnt lgkmcnt(0)
	v_mfma_f32_16x16x32_bf16 v[60:63], v[166:169], v[204:207], v[60:63]
	v_mfma_f32_16x16x32_bf16 v[56:59], v[180:183], v[204:207], v[56:59]
	v_mfma_f32_16x16x32_bf16 v[52:55], v[166:169], v[212:215], v[52:55]
	v_mfma_f32_16x16x32_bf16 v[44:47], v[180:183], v[212:215], v[44:47]
	v_mfma_f32_16x16x32_bf16 v[36:39], v[166:169], v[220:223], v[36:39]
	v_mfma_f32_16x16x32_bf16 v[28:31], v[180:183], v[220:223], v[28:31]
	v_mfma_f32_16x16x32_bf16 v[20:23], v[166:169], v[228:231], v[20:23]
	v_mfma_f32_16x16x32_bf16 v[12:15], v[180:183], v[228:231], v[12:15]
	s_setprio 0
	s_setprio 1
	v_mfma_f32_16x16x32_bf16 v[60:63], v[170:173], v[208:211], v[60:63]
	v_mfma_f32_16x16x32_bf16 v[56:59], v[184:187], v[208:211], v[56:59]
	v_mfma_f32_16x16x32_bf16 v[52:55], v[170:173], v[216:219], v[52:55]
	v_mfma_f32_16x16x32_bf16 v[44:47], v[184:187], v[216:219], v[44:47]
	v_mfma_f32_16x16x32_bf16 v[36:39], v[170:173], v[224:227], v[36:39]
	v_mfma_f32_16x16x32_bf16 v[28:31], v[184:187], v[224:227], v[28:31]
	v_mfma_f32_16x16x32_bf16 v[20:23], v[170:173], v[232:235], v[20:23]
	v_mfma_f32_16x16x32_bf16 v[12:15], v[184:187], v[232:235], v[12:15]
	s_setprio 0
	s_setprio 1
	v_mfma_f32_16x16x32_bf16 v[48:51], v[188:191], v[204:207], v[48:51]
	v_mfma_f32_16x16x32_bf16 v[40:43], v[196:199], v[204:207], v[40:43]
	v_mfma_f32_16x16x32_bf16 v[32:35], v[188:191], v[212:215], v[32:35]
	v_mfma_f32_16x16x32_bf16 v[24:27], v[196:199], v[212:215], v[24:27]
	v_mfma_f32_16x16x32_bf16 v[16:19], v[188:191], v[220:223], v[16:19]
	v_mfma_f32_16x16x32_bf16 v[8:11], v[196:199], v[220:223], v[8:11]
	v_mfma_f32_16x16x32_bf16 v[4:7], v[188:191], v[228:231], v[4:7]
	v_mfma_f32_16x16x32_bf16 v[0:3], v[196:199], v[228:231], v[0:3]
	s_setprio 0
	s_setprio 1
	v_mfma_f32_16x16x32_bf16 v[48:51], v[192:195], v[208:211], v[48:51]
	v_mfma_f32_16x16x32_bf16 v[40:43], v[200:203], v[208:211], v[40:43]
	v_mfma_f32_16x16x32_bf16 v[32:35], v[192:195], v[216:219], v[32:35]
	v_mfma_f32_16x16x32_bf16 v[24:27], v[200:203], v[216:219], v[24:27]
	v_mfma_f32_16x16x32_bf16 v[16:19], v[192:195], v[224:227], v[16:19]
	v_mfma_f32_16x16x32_bf16 v[8:11], v[200:203], v[224:227], v[8:11]
	v_mfma_f32_16x16x32_bf16 v[4:7], v[192:195], v[232:235], v[4:7]
	v_mfma_f32_16x16x32_bf16 v[0:3], v[200:203], v[232:235], v[0:3]
	s_setprio 0
	s_barrier
	s_add_i32 s28, 0, 0x18000
	v_add_u32_e32 v140, s28, v161
	s_add_i32 s29, 0, 0x1c000
	ds_read_b128 v[166:169], v140
	ds_read_b128 v[170:173], v140 offset:1024
	ds_read_b128 v[180:183], v140 offset:2048
	ds_read_b128 v[184:187], v140 offset:3072
	v_add_u32_e32 v140, s29, v161
	ds_read_b128 v[188:191], v140
	ds_read_b128 v[192:195], v140 offset:1024
	ds_read_b128 v[196:199], v140 offset:2048
	ds_read_b128 v[200:203], v140 offset:3072
	s_add_u32 s26, s98, 0x40000
	s_addc_u32 s27, s99, 0
	s_mov_b32 m0, s11
	v_lshl_add_u64 v[242:243], s[26:27], 0, v[138:139]
	ds_read_b128 v[204:207], v165 offset:32768
	ds_read_b128 v[208:211], v165 offset:33792
	ds_read_b128 v[212:215], v165 offset:34816
	ds_read_b128 v[216:219], v165 offset:35840
	ds_read_b128 v[220:223], v165 offset:36864
	ds_read_b128 v[224:227], v165 offset:37888
	ds_read_b128 v[228:231], v165 offset:38912
	ds_read_b128 v[232:235], v165 offset:39936
	global_load_lds_dwordx4 v[242:243], off
	v_lshl_add_u64 v[242:243], s[26:27], 0, v[134:135]
	s_mov_b32 m0, s12
	s_nop 0
	global_load_lds_dwordx4 v[242:243], off
	s_waitcnt vmcnt(8)
	s_waitcnt lgkmcnt(0)
	s_barrier
	s_setprio 1
	s_waitcnt lgkmcnt(0)
	v_mfma_f32_16x16x32_bf16 v[124:127], v[166:169], v[204:207], v[124:127]
	v_mfma_f32_16x16x32_bf16 v[120:123], v[180:183], v[204:207], v[120:123]
	v_mfma_f32_16x16x32_bf16 v[116:119], v[166:169], v[212:215], v[116:119]
	v_mfma_f32_16x16x32_bf16 v[108:111], v[180:183], v[212:215], v[108:111]
	v_mfma_f32_16x16x32_bf16 v[100:103], v[166:169], v[220:223], v[100:103]
	v_mfma_f32_16x16x32_bf16 v[92:95], v[180:183], v[220:223], v[92:95]
	v_mfma_f32_16x16x32_bf16 v[84:87], v[166:169], v[228:231], v[84:87]
	v_mfma_f32_16x16x32_bf16 v[76:79], v[180:183], v[228:231], v[76:79]
	s_setprio 0
	s_setprio 1
	v_mfma_f32_16x16x32_bf16 v[124:127], v[170:173], v[208:211], v[124:127]
	v_mfma_f32_16x16x32_bf16 v[120:123], v[184:187], v[208:211], v[120:123]
	v_mfma_f32_16x16x32_bf16 v[116:119], v[170:173], v[216:219], v[116:119]
	v_mfma_f32_16x16x32_bf16 v[108:111], v[184:187], v[216:219], v[108:111]
	v_mfma_f32_16x16x32_bf16 v[100:103], v[170:173], v[224:227], v[100:103]
	v_mfma_f32_16x16x32_bf16 v[92:95], v[184:187], v[224:227], v[92:95]
	v_mfma_f32_16x16x32_bf16 v[84:87], v[170:173], v[232:235], v[84:87]
	v_mfma_f32_16x16x32_bf16 v[76:79], v[184:187], v[232:235], v[76:79]
	s_setprio 0
	s_setprio 1
	v_mfma_f32_16x16x32_bf16 v[112:115], v[188:191], v[204:207], v[112:115]
	v_mfma_f32_16x16x32_bf16 v[104:107], v[196:199], v[204:207], v[104:107]
	v_mfma_f32_16x16x32_bf16 v[96:99], v[188:191], v[212:215], v[96:99]
	v_mfma_f32_16x16x32_bf16 v[88:91], v[196:199], v[212:215], v[88:91]
	v_mfma_f32_16x16x32_bf16 v[80:83], v[188:191], v[220:223], v[80:83]
	v_mfma_f32_16x16x32_bf16 v[72:75], v[196:199], v[220:223], v[72:75]
	v_mfma_f32_16x16x32_bf16 v[68:71], v[188:191], v[228:231], v[68:71]
	v_mfma_f32_16x16x32_bf16 v[64:67], v[196:199], v[228:231], v[64:67]
	s_setprio 0
	s_setprio 1
	v_mfma_f32_16x16x32_bf16 v[112:115], v[192:195], v[208:211], v[112:115]
	v_mfma_f32_16x16x32_bf16 v[104:107], v[200:203], v[208:211], v[104:107]
	v_mfma_f32_16x16x32_bf16 v[96:99], v[192:195], v[216:219], v[96:99]
	v_mfma_f32_16x16x32_bf16 v[88:91], v[200:203], v[216:219], v[88:91]
	v_mfma_f32_16x16x32_bf16 v[80:83], v[192:195], v[224:227], v[80:83]
	v_mfma_f32_16x16x32_bf16 v[72:75], v[200:203], v[224:227], v[72:75]
	v_mfma_f32_16x16x32_bf16 v[68:71], v[192:195], v[232:235], v[68:71]
	v_mfma_f32_16x16x32_bf16 v[64:67], v[200:203], v[232:235], v[64:67]
	s_setprio 0
	s_barrier
; #define PG8_STAGE(bufoff, gbase, voff) do { _Pragma("unroll") for (int _i = 0; _i < 2; ++_i) \
;         __builtin_amdgcn_global_load_lds((const unsigned*)((const char*)(gbase) + (voff)[_i]), (PG8_LAS unsigned*)(lds + (bufoff) + ldsw + _i * 8192), 16, 0, 0); } while (0)
; #define PG8_LDA(dst, b, h) do { _Pragma("unroll") for (int m = 0; m < 4; ++m) _Pragma("unroll") for (int k = 0; k < 2; ++k) dst[m][k] = *(const PG8_LAS bf16x8*)(lds + PG8_SA(b, h) + aoff + m * 2048 + k * 1024); } while (0)
; #define PG8_MMA(ai, bj, At, Bt) do { __builtin_amdgcn_s_setprio(1); _Pragma("unroll") for (int m = 0; m < 4; ++m) _Pragma("unroll") for (int n = 0; n < 2; ++n) _Pragma("unroll") for (int k = 0; k < 2; ++k) \
;         acc[ai][bj][m][n] = __builtin_amdgcn_mfma_f32_16x16x32_bf16(Bt[n][k], At[m][k], acc[ai][bj][m][n], 0, 0, 0); __builtin_amdgcn_s_setprio(0); } while (0)
; #define PG8_WAIT_V(n) asm volatile("s_waitcnt vmcnt(" #n ")" ::: "memory")
; #define PG8_WAIT_L(n) asm volatile("s_waitcnt lgkmcnt(" #n ")" ::: "memory")
; #define PG8_BAR __builtin_amdgcn_s_barrier()
; #define PG8_SCHED __builtin_amdgcn_sched_barrier(0)
; template <class Epi, class Sched, bool ALIGN_EPI = false, bool SP2 = false, bool ABLK = false>
; __device__ __forceinline__ void gemm_phase(PG8_LAS unsigned char* lds, const Gemm g, const Sched& S, const Epi& E) {
;     ...
;         for (int t = 0; t < nt; t += 2) {
;     ...
;             PG8_LDA(At, 1, 1); PG8_STAGE(PG8_SB(1, 0), b3, voffB); PG8_STAGE(PG8_SB(1, 1), b3 + hstep, voffB); PG8_STAGE(PG8_SA(1, 0), a3, voffA);
;             PG8_WAIT_V(8); PG8_WAIT_L(0); PG8_BAR; PG8_MMA(1, 0, At, B0); PG8_MMA(1, 1, At, B1); PG8_BAR; PG8_SCHED;
	s_add_i32 s26, s28, s46
	v_lshl_add_u64 v[176:177], v[176:177], 0, s[52:53]
	s_mov_b32 m0, s26
	ds_read_b128 v[204:207], v165 offset:49152
	ds_read_b128 v[208:211], v165 offset:50176
	ds_read_b128 v[212:215], v165 offset:51200
	ds_read_b128 v[216:219], v165 offset:52224
	ds_read_b128 v[220:223], v165 offset:53248
	ds_read_b128 v[224:227], v165 offset:54272
	ds_read_b128 v[228:231], v165 offset:55296
	ds_read_b128 v[232:235], v165 offset:56320
	global_load_lds_dwordx4 v[176:177], off
	s_add_i32 m0, s26, 0x2000
	s_add_u32 s0, s0, 0x40080
	v_lshl_add_u64 v[176:177], v[236:237], 0, s[52:53]
	s_addc_u32 s1, s1, 0
	s_add_i32 s26, s29, s46
	global_load_lds_dwordx4 v[176:177], off
	v_lshl_add_u64 v[176:177], s[0:1], 0, v[136:137]
	s_mov_b32 m0, s26
	s_nop 0
	global_load_lds_dwordx4 v[176:177], off
	v_lshl_add_u64 v[176:177], s[0:1], 0, v[132:133]
	s_add_i32 m0, s26, 0x2000
	s_nop 0
	global_load_lds_dwordx4 v[176:177], off
	v_lshl_add_u64 v[176:177], v[238:239], 0, s[52:53]
	s_mov_b32 m0, s14
	s_nop 0
	global_load_lds_dwordx4 v[176:177], off
	v_lshl_add_u64 v[176:177], v[240:241], 0, s[52:53]
	s_mov_b32 m0, s15
	s_nop 0
	global_load_lds_dwordx4 v[176:177], off
	s_waitcnt vmcnt(8)
	s_waitcnt lgkmcnt(0)
	s_barrier
	s_setprio 1
	s_waitcnt lgkmcnt(0)
	v_mfma_f32_16x16x32_bf16 v[60:63], v[166:169], v[204:207], v[60:63]
	v_mfma_f32_16x16x32_bf16 v[56:59], v[180:183], v[204:207], v[56:59]
	v_mfma_f32_16x16x32_bf16 v[52:55], v[166:169], v[212:215], v[52:55]
	v_mfma_f32_16x16x32_bf16 v[44:47], v[180:183], v[212:215], v[44:47]
	v_mfma_f32_16x16x32_bf16 v[36:39], v[166:169], v[220:223], v[36:39]
	v_mfma_f32_16x16x32_bf16 v[28:31], v[180:183], v[220:223], v[28:31]
	v_mfma_f32_16x16x32_bf16 v[20:23], v[166:169], v[228:231], v[20:23]
	v_mfma_f32_16x16x32_bf16 v[12:15], v[180:183], v[228:231], v[12:15]
	s_setprio 0
	s_setprio 1
	v_mfma_f32_16x16x32_bf16 v[60:63], v[170:173], v[208:211], v[60:63]
	v_mfma_f32_16x16x32_bf16 v[56:59], v[184:187], v[208:211], v[56:59]
	v_mfma_f32_16x16x32_bf16 v[52:55], v[170:173], v[216:219], v[52:55]
	v_mfma_f32_16x16x32_bf16 v[44:47], v[184:187], v[216:219], v[44:47]
	v_mfma_f32_16x16x32_bf16 v[36:39], v[170:173], v[224:227], v[36:39]
	v_mfma_f32_16x16x32_bf16 v[28:31], v[184:187], v[224:227], v[28:31]
	v_mfma_f32_16x16x32_bf16 v[20:23], v[170:173], v[232:235], v[20:23]
	v_mfma_f32_16x16x32_bf16 v[12:15], v[184:187], v[232:235], v[12:15]
	s_setprio 0
	s_setprio 1
	v_mfma_f32_16x16x32_bf16 v[48:51], v[188:191], v[204:207], v[48:51]
	v_mfma_f32_16x16x32_bf16 v[40:43], v[196:199], v[204:207], v[40:43]
	v_mfma_f32_16x16x32_bf16 v[32:35], v[188:191], v[212:215], v[32:35]
	v_mfma_f32_16x16x32_bf16 v[24:27], v[196:199], v[212:215], v[24:27]
	v_mfma_f32_16x16x32_bf16 v[16:19], v[188:191], v[220:223], v[16:19]
	v_mfma_f32_16x16x32_bf16 v[8:11], v[196:199], v[220:223], v[8:11]
	v_mfma_f32_16x16x32_bf16 v[4:7], v[188:191], v[228:231], v[4:7]
	v_mfma_f32_16x16x32_bf16 v[0:3], v[196:199], v[228:231], v[0:3]
	s_setprio 0
	s_setprio 1
	v_mfma_f32_16x16x32_bf16 v[48:51], v[192:195], v[208:211], v[48:51]
	v_mfma_f32_16x16x32_bf16 v[40:43], v[200:203], v[208:211], v[40:43]
	v_mfma_f32_16x16x32_bf16 v[32:35], v[192:195], v[216:219], v[32:35]
	v_mfma_f32_16x16x32_bf16 v[24:27], v[200:203], v[216:219], v[24:27]
	v_mfma_f32_16x16x32_bf16 v[16:19], v[192:195], v[224:227], v[16:19]
	v_mfma_f32_16x16x32_bf16 v[8:11], v[200:203], v[224:227], v[8:11]
	v_mfma_f32_16x16x32_bf16 v[4:7], v[192:195], v[232:235], v[4:7]
	v_mfma_f32_16x16x32_bf16 v[0:3], v[200:203], v[232:235], v[0:3]
	s_setprio 0
	s_barrier
	s_add_i32 s25, s25, 2
	s_add_u32 vcc_lo, vcc_lo, 0x100
	s_addc_u32 vcc_hi, vcc_hi, 0
	s_add_u32 s23, s23, 0x100
	s_addc_u32 s24, s24, 0
	s_cmp_gt_u32 s25, 13
	s_cbranch_scc0 .LBB0_215
